# diff attention fast path: softmax row sums via packed f32 add trees
# speedup vs baseline: 1.0036x; 1.0019x over previous
.LBB0_348:
	v_pk_add_f32 v[96:97], v[96:97], v[98:99]
	v_pk_add_f32 v[100:101], v[100:101], v[102:103]
	v_pk_add_f32 v[104:105], v[104:105], v[106:107]
	v_pk_add_f32 v[108:109], v[108:109], v[110:111]
	v_exp_f32_e32 v80, v80
	v_exp_f32_e32 v81, v81
	v_pk_add_f32 v[96:97], v[96:97], v[100:101]
	v_exp_f32_e32 v82, v82
	v_pk_add_f32 v[104:105], v[104:105], v[108:109]
	v_exp_f32_e32 v83, v83
	v_exp_f32_e32 v84, v84
	v_exp_f32_e32 v85, v85
	v_pk_add_f32 v[96:97], v[96:97], v[104:105]
	v_exp_f32_e32 v86, v86
	v_exp_f32_e32 v87, v87
	v_add_f32_e32 v96, v96, v97
	v_add_f32_e32 v188, v188, v96
	v_pk_add_f32 v[96:97], v[80:81], v[82:83]
	v_pk_add_f32 v[98:99], v[84:85], v[86:87]
	v_cvt_pk_bf16_f32 v80, v80, v81
	v_cvt_pk_bf16_f32 v81, v82, v83
	v_cvt_pk_bf16_f32 v82, v84, v85
	v_cvt_pk_bf16_f32 v83, v86, v87
	v_exp_f32_e32 v88, v88
	v_pk_add_f32 v[96:97], v[96:97], v[98:99]
	v_mfma_f32_32x32x16_bf16 v[64:79], v[136:139], v[80:83], v[64:79]
	v_exp_f32_e32 v89, v89
	v_exp_f32_e32 v90, v90
	v_exp_f32_e32 v91, v91
	v_exp_f32_e32 v92, v92
	v_exp_f32_e32 v93, v93
	v_exp_f32_e32 v94, v94
	v_exp_f32_e32 v95, v95
	v_mfma_f32_32x32x16_bf16 v[32:47], v[10:13], v[80:83], v[32:47]
	v_pk_add_f32 v[98:99], v[88:89], v[90:91]
	v_pk_add_f32 v[100:101], v[92:93], v[94:95]
	v_cvt_pk_bf16_f32 v10, v88, v89
	v_cvt_pk_bf16_f32 v11, v90, v91
	v_cvt_pk_bf16_f32 v12, v92, v93
	v_cvt_pk_bf16_f32 v13, v94, v95
	v_pk_add_f32 v[96:97], v[96:97], v[98:99]
	v_pk_add_f32 v[96:97], v[96:97], v[100:101]
	v_mfma_f32_32x32x16_bf16 v[64:79], v[6:9], v[10:13], v[64:79]
	v_add_f32_e32 v96, v96, v97
	s_sub_i32 s0, s0, 64
	v_add_f32_e32 v181, v181, v96
	v_mfma_f32_32x32x16_bf16 v[32:47], v[2:5], v[10:13], v[32:47]
	v_add_u32_e32 v0, 0xffffee00, v0
	v_subrev_u32_e32 v15, 32, v15
	s_cmpk_eq_i32 s0, 0xff80
	s_cbranch_scc1 .LBB0_353
